# v24: v23 + next-item L2 prefetch in the phase-A weight-conversion loop
# baseline (speedup 1.0000x reference)
.LBB0_180:
	s_ashr_i32 s37, s36, 31
	s_and_b32 s30, s6, 0x3c0
	s_lshl_b64 s[34:35], s[36:37], 2
	s_add_u32 s34, s40, s34
	v_lshlrev_b32_e32 v2, 4, v1
	s_addc_u32 s35, s41, s35
	v_and_b32_e32 v6, 0xf0, v2
	v_mov_b32_e32 v7, v0
	v_lshl_add_u64 v[8:9], s[34:35], 0, v[6:7]
	v_ashrrev_i32_e32 v7, 4, v1
	v_add_u32_e32 v2, s30, v7
	v_ashrrev_i32_e32 v3, 31, v2
	v_mul_lo_u32 v4, s42, v3
	v_mul_lo_u32 v5, s43, v2
	v_mad_u64_u32 v[2:3], s[34:35], s42, v2, 0
	v_add3_u32 v3, v3, v4, v5
	v_lshl_add_u64 v[2:3], v[2:3], 2, v[8:9]
	s_cmpk_lt_i32 s18, 0xa00
	s_cselect_b32 s100, 0x1000, 0
	s_mov_b32 s101, 0
	v_lshl_add_u64 v[204:205], v[2:3], 0, s[100:101]
	global_load_dwordx4 v[2:5], v[2:3], off
	v_add_u32_e32 v10, 0x200, v1
	v_ashrrev_i32_e32 v14, 4, v10
	v_add_u32_e32 v6, s33, v6
	v_add_u32_e32 v12, s30, v14
	s_movk_i32 s36, 0x104
	v_mad_u64_u32 v[10:11], s[34:35], v7, s36, v[6:7]
	v_ashrrev_i32_e32 v7, 31, v12
	v_mul_lo_u32 v11, s43, v12
	v_mad_u64_u32 v[12:13], s[34:35], s42, v12, 0
	v_mul_lo_u32 v7, s42, v7
	v_add3_u32 v13, v13, v7, v11
	v_lshl_add_u64 v[8:9], v[12:13], 2, v[8:9]
	global_load_dwordx4 v[200:203], v[8:9], off
	v_lshl_add_u64 v[206:207], v[8:9], 0, s[100:101]
	global_load_dword v224, v[204:205], off
	global_load_dword v224, v[206:207], off
	v_mad_u64_u32 v[6:7], s[34:35], v14, s36, v[6:7]
	s_lshl_b32 s30, s30, 1
	v_mov_b32_e32 v11, v0
	s_add_i32 s18, s18, s20
	s_waitcnt vmcnt(3) lgkmcnt(0)
	ds_write2_b32 v10, v2, v3 offset1:1
	ds_write2_b32 v10, v4, v5 offset0:2 offset1:3
	v_ashrrev_i32_e32 v8, 3, v1
	v_lshlrev_b32_e32 v1, 3, v1
	v_and_b32_e32 v1, 56, v1
	v_lshlrev_b32_e32 v12, 2, v8
	v_mul_u32_u24_e32 v13, 0x104, v1
	v_lshlrev_b32_e32 v10, 1, v1
	v_add3_u32 v1, s33, v13, v12
	v_add_u32_e32 v12, 0x400, v1
	v_ashrrev_i32_e32 v9, 31, v8
	v_lshlrev_b64 v[8:9], 11, v[8:9]
	v_lshl_add_u64 v[8:9], s[26:27], 0, v[8:9]
	v_readlane_b32 s26, v254, 37
	s_add_i32 s6, s6, s26
	v_lshl_add_u64 v[8:9], v[8:9], 0, s[30:31]
	s_cmpk_lt_i32 s18, 0x1100
	v_lshl_add_u64 v[8:9], v[8:9], 0, v[10:11]
	s_waitcnt vmcnt(2) lgkmcnt(0)
	ds_write2_b32 v6, v200, v201 offset1:1
	ds_write2_b32 v6, v202, v203 offset0:2 offset1:3
	s_waitcnt lgkmcnt(0)
	s_barrier
	ds_read2_b32 v[2:3], v1 offset1:65
	ds_read2_b32 v[4:5], v1 offset0:130 offset1:195
	ds_read2_b32 v[6:7], v12 offset0:4 offset1:69
	ds_read2_b32 v[12:13], v12 offset0:134 offset1:199
	s_waitcnt lgkmcnt(3)
	s_nop 1
	v_cvt_pk_bf16_f32 v2, v2, v3
	s_waitcnt lgkmcnt(2)
	s_nop 1
	v_cvt_pk_bf16_f32 v3, v4, v5
	s_waitcnt lgkmcnt(1)
	s_nop 1
	v_cvt_pk_bf16_f32 v4, v6, v7
	s_waitcnt lgkmcnt(0)
	s_nop 1
	v_cvt_pk_bf16_f32 v5, v12, v13
	global_store_dwordx4 v[8:9], v[2:5], off
	s_barrier
	s_cbranch_scc0 .LBB0_189
